# v61 + nt on the P0 f32 weight loads (each weight element is read once)
# speedup vs baseline: 1.0153x; 1.0129x over previous
.LBB0_24:
	s_cmpk_gt_i32 s47, 0x67f
	s_mov_b64 s[0:1], -1
	s_cbranch_scc0 .LBB0_95
	s_cmpk_gt_u32 s47, 0x87f
	s_cbranch_scc0 .LBB0_92
	s_cmpk_gt_u32 s47, 0xa7f
	s_cbranch_scc0 .LBB0_89
	s_cmpk_gt_u32 s47, 0xd7f
	s_cbranch_scc0 .LBB0_69
	s_cmpk_gt_u32 s47, 0xf7f
	s_cbranch_scc0 .LBB0_66
	s_cmpk_gt_u32 s47, 0x107f
	s_cbranch_scc0 .LBB0_63
	s_cmpk_gt_u32 s47, 0x117f
	s_cbranch_scc0 .LBB0_60
	s_cmpk_gt_u32 s47, 0x1c7f
	s_cbranch_scc0 .LBB0_41
	s_cmpk_gt_u32 s47, 0x277f
	s_cbranch_scc0 .LBB0_38
	s_and_b32 s4, s38, 0x3e0
	v_or_b32_e32 v0, s4, v41
	v_or_b32_e32 v1, s4, v43
	v_or_b32_e32 v4, s4, v45
	v_or_b32_e32 v5, s4, v47
	s_cmpk_gt_u32 s47, 0x2cff
	v_lshlrev_b32_e32 v14, 2, v0
	v_or_b32_e32 v3, s4, v12
	v_mul_u32_u24_e32 v2, 0xb00, v1
	v_mul_u32_u24_e32 v1, 0xb00, v4
	v_mul_u32_u24_e32 v0, 0xb00, v5
	s_cbranch_scc0 .LBB0_35
	s_and_b32 s0, s40, 0x1ffc0
	v_or_b32_e32 v65, s0, v45
	v_lshlrev_b32_e32 v66, 12, v65
	v_or_b32_e32 v65, s0, v47
	v_lshlrev_b32_e32 v68, 12, v65
	v_or_b32_e32 v65, s0, v48
	v_or_b32_e32 v4, s0, v12
	v_or_b32_e32 v6, s0, v43
	v_lshlrev_b32_e32 v74, 12, v65
	v_or_b32_e32 v65, s0, v49
	v_lshl_add_u64 v[38:39], s[6:7], 0, v[14:15]
	v_lshlrev_b32_e32 v4, 12, v4
	v_mov_b32_e32 v5, v15
	v_lshlrev_b32_e32 v6, 12, v6
	v_mov_b32_e32 v7, v15
	v_mov_b32_e32 v67, v15
	v_mov_b32_e32 v69, v15
	v_mov_b32_e32 v75, v15
	v_lshlrev_b32_e32 v76, 12, v65
	v_mov_b32_e32 v77, v15
	v_lshl_add_u64 v[4:5], v[38:39], 0, v[4:5]
	v_lshl_add_u64 v[8:9], v[38:39], 0, v[6:7]
	v_lshl_add_u64 v[66:67], v[38:39], 0, v[66:67]
	v_lshl_add_u64 v[70:71], v[38:39], 0, v[68:69]
	v_lshl_add_u64 v[74:75], v[38:39], 0, v[74:75]
	v_lshl_add_u64 v[78:79], v[38:39], 0, v[76:77]
	global_load_dwordx4 v[4:7], v[4:5], off nt
	s_nop 0
	global_load_dwordx4 v[8:11], v[8:9], off nt
	s_nop 0
	global_load_dwordx4 v[66:69], v[66:67], off nt
	s_nop 0
	global_load_dwordx4 v[70:73], v[70:71], off nt
	s_nop 0
	global_load_dwordx4 v[74:77], v[74:75], off nt
	s_nop 0
	global_load_dwordx4 v[78:81], v[78:79], off nt
	v_or_b32_e32 v65, s0, v50
	v_lshlrev_b32_e32 v82, 12, v65
	v_mov_b32_e32 v83, v15
	v_lshl_add_u64 v[82:83], v[38:39], 0, v[82:83]
	v_or_b32_e32 v65, s0, v51
	global_load_dwordx4 v[82:85], v[82:83], off nt
	v_lshlrev_b32_e32 v86, 12, v65
	v_mov_b32_e32 v87, v15
	v_lshl_add_u64 v[38:39], v[38:39], 0, v[86:87]
	global_load_dwordx4 v[86:89], v[38:39], off nt
	v_add_u32_e32 v65, 0x18c0, v53
	v_add_u32_e32 v94, 0x18c8, v53
	v_add_u32_e32 v95, 0x1ce0, v53
	v_add_u32_e32 v96, 0x1ce8, v53
	v_mul_u32_u24_e32 v38, 0xb00, v3
	s_lshl_b32 s28, s0, 1
	v_mov_b32_e32 v39, v15
	v_lshlrev_b32_e32 v38, 1, v38
	v_lshl_add_u64 v[92:93], v[16:17], 0, s[28:29]
	v_lshl_add_u64 v[38:39], v[92:93], 0, v[38:39]
	v_lshlrev_b32_e32 v90, 1, v2
	v_mov_b32_e32 v91, v15
	v_lshl_add_u64 v[90:91], v[92:93], 0, v[90:91]
	s_mov_b64 s[0:1], 0
	s_waitcnt vmcnt(7)
	ds_write2_b32 v53, v4, v5 offset1:1
	ds_write2_b32 v53, v6, v7 offset0:2 offset1:3
	s_waitcnt vmcnt(6)
	ds_write2_b32 v54, v8, v9 offset1:1
	ds_write2_b32 v55, v10, v11 offset1:1
	s_waitcnt vmcnt(5)
	ds_write2_b32 v56, v66, v67 offset1:1
	ds_write2_b32 v57, v68, v69 offset1:1
	s_waitcnt vmcnt(4)
	ds_write2_b32 v58, v70, v71 offset1:1
	ds_write2_b32 v59, v72, v73 offset1:1
	s_waitcnt vmcnt(3)
	ds_write2_b32 v60, v74, v75 offset1:1
	ds_write2_b32 v61, v76, v77 offset1:1
	s_waitcnt vmcnt(2)
	ds_write2_b32 v62, v78, v79 offset1:1
	ds_write2_b32 v63, v80, v81 offset1:1
	s_waitcnt vmcnt(1)
	ds_write2_b32 v65, v82, v83 offset1:1
	ds_write2_b32 v94, v84, v85 offset1:1
	s_waitcnt vmcnt(0)
	ds_write2_b32 v95, v86, v87 offset1:1
	ds_write2_b32 v96, v88, v89 offset1:1
	s_waitcnt lgkmcnt(0)
	ds_read2_b32 v[8:9], v52 offset0:33 offset1:41
	ds_read2_b32 v[10:11], v52 offset1:8
	ds_read2_b32 v[66:67], v52 offset0:66 offset1:74
	ds_read2_b32 v[68:69], v52 offset0:99 offset1:107
	ds_read2_b32 v[70:71], v52 offset0:132 offset1:140
	ds_read2_b32 v[72:73], v52 offset0:165 offset1:173
	ds_read2_b32 v[74:75], v52 offset0:198 offset1:206
	ds_read2_b32 v[76:77], v52 offset0:231 offset1:239
	ds_read2_b32 v[78:79], v52 offset0:16 offset1:24
	ds_read2_b32 v[80:81], v52 offset0:49 offset1:57
	ds_read2_b32 v[82:83], v52 offset0:82 offset1:90
	ds_read2_b32 v[84:85], v52 offset0:115 offset1:123
	s_waitcnt lgkmcnt(10)
	v_cvt_pk_bf16_f32 v4, v10, v8
	s_waitcnt lgkmcnt(8)
	v_cvt_pk_bf16_f32 v5, v66, v68
	s_waitcnt lgkmcnt(6)
	v_cvt_pk_bf16_f32 v6, v70, v72
	s_waitcnt lgkmcnt(4)
	v_cvt_pk_bf16_f32 v7, v74, v76
	global_store_dwordx4 v[38:39], v[4:7], off
	v_cvt_pk_bf16_f32 v8, v11, v9
	v_cvt_pk_bf16_f32 v9, v67, v69
	v_cvt_pk_bf16_f32 v10, v71, v73
	ds_read2_b32 v[38:39], v52 offset0:148 offset1:156
	ds_read2_b32 v[66:67], v52 offset0:181 offset1:189
	ds_read2_b32 v[68:69], v52 offset0:214 offset1:222
	ds_read2_b32 v[70:71], v52 offset0:247 offset1:255
	v_cvt_pk_bf16_f32 v11, v75, v77
	global_store_dwordx4 v[90:91], v[8:11], off
	s_waitcnt lgkmcnt(6)
	v_cvt_pk_bf16_f32 v4, v78, v80
	s_waitcnt lgkmcnt(4)
	v_cvt_pk_bf16_f32 v5, v82, v84
	v_lshlrev_b32_e32 v8, 1, v1
	v_mov_b32_e32 v9, v15
	s_waitcnt lgkmcnt(2)
	v_cvt_pk_bf16_f32 v6, v38, v66
	s_waitcnt lgkmcnt(0)
	v_cvt_pk_bf16_f32 v7, v68, v70
	v_lshl_add_u64 v[8:9], v[92:93], 0, v[8:9]
	global_store_dwordx4 v[8:9], v[4:7], off
	v_lshlrev_b32_e32 v8, 1, v0
	v_mov_b32_e32 v9, v15
	v_cvt_pk_bf16_f32 v4, v79, v81
	v_cvt_pk_bf16_f32 v5, v83, v85
	v_cvt_pk_bf16_f32 v6, v39, v67
	v_cvt_pk_bf16_f32 v7, v69, v71
	v_lshl_add_u64 v[8:9], v[92:93], 0, v[8:9]
	global_store_dwordx4 v[8:9], v[4:7], off
	s_waitcnt lgkmcnt(0)
.LBB0_35:
	s_andn2_b64 vcc, exec, s[0:1]
	s_cbranch_vccnz .LBB0_37
	s_add_i32 s0, s40, 0xb00
	s_and_b32 s0, s0, 0x1ffc0
	s_mov_b64 s[4:5], s[50:51]
	v_readlane_b32 s48, v250, 5
	v_readlane_b32 s54, v250, 11
	v_readlane_b32 s55, v250, 12
	v_or_b32_e32 v4, s0, v12
	v_or_b32_e32 v6, s0, v43
	v_lshl_add_u64 v[38:39], s[54:55], 0, v[14:15]
	v_lshlrev_b32_e32 v14, 12, v4
	v_lshl_add_u64 v[4:5], v[38:39], 0, v[14:15]
	v_lshlrev_b32_e32 v14, 12, v6
	v_lshl_add_u64 v[8:9], v[38:39], 0, v[14:15]
	v_or_b32_e32 v14, s0, v45
	v_lshlrev_b32_e32 v14, 12, v14
	v_lshl_add_u64 v[66:67], v[38:39], 0, v[14:15]
	v_or_b32_e32 v14, s0, v47
	v_lshlrev_b32_e32 v14, 12, v14
	v_lshl_add_u64 v[70:71], v[38:39], 0, v[14:15]
	v_or_b32_e32 v14, s0, v48
	v_lshlrev_b32_e32 v14, 12, v14
	v_lshl_add_u64 v[74:75], v[38:39], 0, v[14:15]
	v_or_b32_e32 v14, s0, v49
	v_lshlrev_b32_e32 v14, 12, v14
	v_lshl_add_u64 v[78:79], v[38:39], 0, v[14:15]
	global_load_dwordx4 v[4:7], v[4:5], off nt
	s_nop 0
	global_load_dwordx4 v[8:11], v[8:9], off nt
	s_nop 0
	global_load_dwordx4 v[66:69], v[66:67], off nt
	s_nop 0
	global_load_dwordx4 v[70:73], v[70:71], off nt
	s_nop 0
	global_load_dwordx4 v[74:77], v[74:75], off nt
	s_nop 0
	global_load_dwordx4 v[78:81], v[78:79], off nt
	v_or_b32_e32 v14, s0, v50
	v_lshlrev_b32_e32 v14, 12, v14
	v_lshl_add_u64 v[82:83], v[38:39], 0, v[14:15]
	v_or_b32_e32 v14, s0, v51
	global_load_dwordx4 v[82:85], v[82:83], off nt
	v_lshlrev_b32_e32 v14, 12, v14
	v_lshl_add_u64 v[38:39], v[38:39], 0, v[14:15]
	global_load_dwordx4 v[86:89], v[38:39], off nt
	v_add_u32_e32 v65, 0x18c0, v53
	v_add_u32_e32 v96, 0x18c8, v53
	v_add_u32_e32 v97, 0x1ce0, v53
	v_add_u32_e32 v98, 0x1ce8, v53
	v_mul_u32_u24_e32 v3, 0xb00, v3
	s_lshl_b32 s28, s0, 1
	v_lshl_add_u64 v[38:39], v[18:19], 0, s[28:29]
	v_lshlrev_b32_e32 v14, 1, v3
	v_lshl_add_u64 v[90:91], v[38:39], 0, v[14:15]
	v_lshlrev_b32_e32 v14, 1, v2
	v_lshl_add_u64 v[92:93], v[38:39], 0, v[14:15]
	v_lshlrev_b32_e32 v14, 1, v1
	v_lshl_add_u64 v[94:95], v[38:39], 0, v[14:15]
	v_lshlrev_b32_e32 v14, 1, v0
	v_readlane_b32 s50, v250, 7
	v_readlane_b32 s51, v250, 8
	s_mov_b64 s[50:51], s[4:5]
	v_readlane_b32 s49, v250, 6
	v_readlane_b32 s52, v250, 9
	v_readlane_b32 s53, v250, 10
	s_waitcnt vmcnt(7)
	ds_write2_b32 v53, v4, v5 offset1:1
	ds_write2_b32 v53, v6, v7 offset0:2 offset1:3
	s_waitcnt vmcnt(6)
	ds_write2_b32 v54, v8, v9 offset1:1
	ds_write2_b32 v55, v10, v11 offset1:1
	s_waitcnt vmcnt(5)
	ds_write2_b32 v56, v66, v67 offset1:1
	ds_write2_b32 v57, v68, v69 offset1:1
	s_waitcnt vmcnt(4)
	ds_write2_b32 v58, v70, v71 offset1:1
	ds_write2_b32 v59, v72, v73 offset1:1
	s_waitcnt vmcnt(3)
	ds_write2_b32 v60, v74, v75 offset1:1
	ds_write2_b32 v61, v76, v77 offset1:1
	s_waitcnt vmcnt(2)
	ds_write2_b32 v62, v78, v79 offset1:1
	ds_write2_b32 v63, v80, v81 offset1:1
	s_waitcnt vmcnt(1)
	ds_write2_b32 v65, v82, v83 offset1:1
	ds_write2_b32 v96, v84, v85 offset1:1
	s_waitcnt vmcnt(0)
	ds_write2_b32 v97, v86, v87 offset1:1
	ds_write2_b32 v98, v88, v89 offset1:1
	s_waitcnt lgkmcnt(0)
	ds_read2_b32 v[4:5], v52 offset0:33 offset1:41
	ds_read2_b32 v[6:7], v52 offset1:8
	ds_read2_b32 v[8:9], v52 offset0:66 offset1:74
	ds_read2_b32 v[10:11], v52 offset0:99 offset1:107
	ds_read2_b32 v[66:67], v52 offset0:132 offset1:140
	ds_read2_b32 v[68:69], v52 offset0:165 offset1:173
	ds_read2_b32 v[70:71], v52 offset0:198 offset1:206
	ds_read2_b32 v[72:73], v52 offset0:231 offset1:239
	ds_read2_b32 v[74:75], v52 offset0:16 offset1:24
	ds_read2_b32 v[76:77], v52 offset0:49 offset1:57
	ds_read2_b32 v[78:79], v52 offset0:82 offset1:90
	ds_read2_b32 v[80:81], v52 offset0:115 offset1:123
	ds_read2_b32 v[82:83], v52 offset0:148 offset1:156
	ds_read2_b32 v[84:85], v52 offset0:181 offset1:189
	ds_read2_b32 v[86:87], v52 offset0:214 offset1:222
	ds_read2_b32 v[88:89], v52 offset0:247 offset1:255
	s_waitcnt lgkmcnt(14)
	v_cvt_pk_bf16_f32 v0, v6, v4
	s_waitcnt lgkmcnt(12)
	v_cvt_pk_bf16_f32 v1, v8, v10
	s_waitcnt lgkmcnt(10)
	v_cvt_pk_bf16_f32 v2, v66, v68
	s_waitcnt lgkmcnt(8)
	v_cvt_pk_bf16_f32 v3, v70, v72
	v_cvt_pk_bf16_f32 v4, v7, v5
	v_cvt_pk_bf16_f32 v5, v9, v11
	v_cvt_pk_bf16_f32 v6, v67, v69
	v_cvt_pk_bf16_f32 v7, v71, v73
	s_waitcnt lgkmcnt(6)
	v_cvt_pk_bf16_f32 v8, v74, v76
	s_waitcnt lgkmcnt(4)
	v_cvt_pk_bf16_f32 v9, v78, v80
	s_waitcnt lgkmcnt(2)
	v_cvt_pk_bf16_f32 v10, v82, v84
	s_waitcnt lgkmcnt(0)
	v_cvt_pk_bf16_f32 v11, v86, v88
	v_cvt_pk_bf16_f32 v66, v75, v77
	v_cvt_pk_bf16_f32 v67, v79, v81
	v_cvt_pk_bf16_f32 v68, v83, v85
	v_cvt_pk_bf16_f32 v69, v87, v89
	global_store_dwordx4 v[90:91], v[0:3], off
	global_store_dwordx4 v[92:93], v[4:7], off
	global_store_dwordx4 v[94:95], v[8:11], off
	v_lshl_add_u64 v[0:1], v[38:39], 0, v[14:15]
	global_store_dwordx4 v[0:1], v[66:69], off
	s_waitcnt lgkmcnt(0)

.LBB0_38:
	s_andn2_b64 vcc, exec, s[0:1]
	s_cbranch_vccnz .LBB0_40
	s_add_i32 s0, s47, 0xe380
	s_and_b32 s1, s0, 0xffff
	s_mul_i32 s1, s1, 0xba2f
	s_lshr_b32 s1, s1, 23
	s_mul_i32 s4, s1, 0xb0
	s_sub_i32 s4, s0, s4
	s_and_b32 s0, s4, 0xffff
	s_bfe_i32 s5, s4, 0x10002
	s_lshl_b32 s4, s4, 4
	s_lshl_b32 s0, s0, 5
	s_and_b32 s5, s5, 0xb00
	s_and_b32 s4, s4, 0xf80
	s_add_i32 s5, s5, s4
	s_and_b32 s4, s0, 0x60
	s_or_b32 s4, s5, s4
	v_or_b32_e32 v0, s4, v41
	s_lshl_b32 s28, s1, 6
	v_lshlrev_b32_e32 v14, 2, v0
	v_lshl_add_u64 v[38:39], s[78:79], 0, v[14:15]
	v_or_b32_e32 v4, s28, v12
	v_mad_u64_u32 v[0:1], s[4:5], v4, s44, v[38:39]
	v_lshlrev_b32_e32 v4, 2, v4
	v_or_b32_e32 v8, s28, v43
	global_load_dword v14, v4, s[84:85]
	v_mad_u64_u32 v[4:5], s[4:5], v8, s44, v[38:39]
	v_lshlrev_b32_e32 v8, 2, v8
	v_or_b32_e32 v65, s28, v45
	global_load_dword v86, v8, s[84:85]
	v_mad_u64_u32 v[8:9], s[4:5], v65, s44, v[38:39]
	v_lshlrev_b32_e32 v65, 2, v65
	global_load_dword v88, v65, s[84:85]
	v_or_b32_e32 v65, s28, v47
	v_mad_u64_u32 v[66:67], s[4:5], v65, s44, v[38:39]
	v_lshlrev_b32_e32 v65, 2, v65
	global_load_dword v90, v65, s[84:85]
	v_or_b32_e32 v65, s28, v48
	v_mad_u64_u32 v[70:71], s[4:5], v65, s44, v[38:39]
	v_lshlrev_b32_e32 v65, 2, v65
	global_load_dword v92, v65, s[84:85]
	v_or_b32_e32 v65, s28, v49
	v_mad_u64_u32 v[74:75], s[4:5], v65, s44, v[38:39]
	v_lshlrev_b32_e32 v65, 2, v65
	global_load_dword v94, v65, s[84:85]
	v_or_b32_e32 v65, s28, v50
	v_mad_u64_u32 v[78:79], s[4:5], v65, s44, v[38:39]
	v_lshlrev_b32_e32 v65, 2, v65
	global_load_dword v96, v65, s[84:85]
	v_or_b32_e32 v65, s28, v51
	global_load_dwordx4 v[0:3], v[0:1], off nt
	v_mad_u64_u32 v[38:39], s[4:5], v65, s44, v[38:39]
	global_load_dwordx4 v[4:7], v[4:5], off nt
	v_lshlrev_b32_e32 v65, 2, v65
	global_load_dwordx4 v[8:11], v[8:9], off nt
	v_add_u32_e32 v87, 0x18c8, v53
	global_load_dwordx4 v[66:69], v[66:67], off nt
	s_lshl_b32 s28, s1, 7
	global_load_dwordx4 v[70:73], v[70:71], off nt
	s_waitcnt vmcnt(4)
	v_pk_mul_f32 v[2:3], v[2:3], v[14:15] op_sel_hi:[1,0]
	global_load_dwordx4 v[74:77], v[74:75], off nt
	v_pk_mul_f32 v[0:1], v[0:1], v[14:15] op_sel_hi:[1,0]
	global_load_dwordx4 v[78:81], v[78:79], off nt
	s_nop 0
	global_load_dword v98, v65, s[84:85]
	global_load_dwordx4 v[82:85], v[38:39], off nt
	s_waitcnt vmcnt(7)
	v_pk_mul_f32 v[4:5], v[4:5], v[86:87] op_sel_hi:[1,0]
	v_add_u32_e32 v65, 0x18c0, v53
	v_pk_mul_f32 v[6:7], v[6:7], v[86:87] op_sel_hi:[1,0]
	s_waitcnt vmcnt(6)
	v_pk_mul_f32 v[10:11], v[10:11], v[88:89] op_sel_hi:[1,0]
	v_pk_mul_f32 v[8:9], v[8:9], v[88:89] op_sel_hi:[1,0]
	s_waitcnt vmcnt(5)
	v_pk_mul_f32 v[38:39], v[68:69], v[90:91] op_sel_hi:[1,0]
	v_pk_mul_f32 v[66:67], v[66:67], v[90:91] op_sel_hi:[1,0]
	s_waitcnt vmcnt(4)
	v_pk_mul_f32 v[68:69], v[72:73], v[92:93] op_sel_hi:[1,0]
	v_pk_mul_f32 v[70:71], v[70:71], v[92:93] op_sel_hi:[1,0]
	s_waitcnt vmcnt(3)
	v_pk_mul_f32 v[72:73], v[76:77], v[94:95] op_sel_hi:[1,0]
	v_pk_mul_f32 v[74:75], v[74:75], v[94:95] op_sel_hi:[1,0]
	s_waitcnt vmcnt(2)
	v_pk_mul_f32 v[76:77], v[80:81], v[96:97] op_sel_hi:[1,0]
	v_pk_mul_f32 v[78:79], v[78:79], v[96:97] op_sel_hi:[1,0]
	ds_write2_b32 v53, v0, v1 offset1:1
	ds_write2_b32 v53, v2, v3 offset0:2 offset1:3
	ds_write2_b32 v54, v4, v5 offset1:1
	ds_write2_b32 v55, v6, v7 offset1:1
	ds_write2_b32 v56, v8, v9 offset1:1
	ds_write2_b32 v57, v10, v11 offset1:1
	ds_write2_b32 v58, v66, v67 offset1:1
	ds_write2_b32 v59, v38, v39 offset1:1
	ds_write2_b32 v60, v70, v71 offset1:1
	ds_write2_b32 v61, v68, v69 offset1:1
	ds_write2_b32 v62, v74, v75 offset1:1
	ds_write2_b32 v63, v72, v73 offset1:1
	ds_write2_b32 v65, v78, v79 offset1:1
	ds_write2_b32 v87, v76, v77 offset1:1
	s_waitcnt vmcnt(0)
	v_pk_mul_f32 v[2:3], v[82:83], v[98:99] op_sel_hi:[1,0]
	v_add_u32_e32 v4, 0x1ce0, v53
	v_pk_mul_f32 v[0:1], v[84:85], v[98:99] op_sel_hi:[1,0]
	ds_write2_b32 v4, v2, v3 offset1:1
	v_add_u32_e32 v2, 0x1ce8, v53
	ds_write2_b32 v2, v0, v1 offset1:1
	s_waitcnt lgkmcnt(0)
	ds_read2_b32 v[4:5], v52 offset0:33 offset1:41
	ds_read2_b32 v[6:7], v52 offset1:8
	ds_read2_b32 v[8:9], v52 offset0:66 offset1:74
	ds_read2_b32 v[10:11], v52 offset0:99 offset1:107
	ds_read2_b32 v[38:39], v52 offset0:132 offset1:140
	ds_read2_b32 v[66:67], v52 offset0:165 offset1:173
	ds_read2_b32 v[68:69], v52 offset0:198 offset1:206
	ds_read2_b32 v[70:71], v52 offset0:231 offset1:239
	s_waitcnt lgkmcnt(6)
	v_cvt_pk_bf16_f32 v0, v6, v4
	v_or_b32_e32 v4, s0, v12
	v_lshl_add_u64 v[72:73], v[20:21], 0, s[28:29]
	v_lshlrev_b32_e32 v14, 11, v4
	s_waitcnt lgkmcnt(4)
	v_cvt_pk_bf16_f32 v1, v8, v10
	s_waitcnt lgkmcnt(2)
	v_cvt_pk_bf16_f32 v2, v38, v66
	s_waitcnt lgkmcnt(0)
	v_cvt_pk_bf16_f32 v3, v68, v70
	v_lshl_add_u64 v[74:75], v[72:73], 0, v[14:15]
	global_store_dwordx4 v[74:75], v[0:3], off
	v_or_b32_e32 v4, s0, v43
	v_lshlrev_b32_e32 v14, 11, v4
	v_cvt_pk_bf16_f32 v0, v7, v5
	v_cvt_pk_bf16_f32 v1, v9, v11
	v_cvt_pk_bf16_f32 v2, v39, v67
	v_cvt_pk_bf16_f32 v3, v69, v71
	ds_read2_b32 v[6:7], v52 offset0:49 offset1:57
	ds_read2_b32 v[8:9], v52 offset0:16 offset1:24
	ds_read2_b32 v[10:11], v52 offset0:82 offset1:90
	ds_read2_b32 v[38:39], v52 offset0:115 offset1:123
	ds_read2_b32 v[66:67], v52 offset0:148 offset1:156
	ds_read2_b32 v[68:69], v52 offset0:181 offset1:189
	ds_read2_b32 v[70:71], v52 offset0:214 offset1:222
	ds_read2_b32 v[74:75], v52 offset0:247 offset1:255
	v_lshl_add_u64 v[4:5], v[72:73], 0, v[14:15]
	global_store_dwordx4 v[4:5], v[0:3], off
	v_or_b32_e32 v4, s0, v45
	v_lshlrev_b32_e32 v14, 11, v4
	s_waitcnt lgkmcnt(6)
	v_cvt_pk_bf16_f32 v0, v8, v6
	s_waitcnt lgkmcnt(4)
	v_cvt_pk_bf16_f32 v1, v10, v38
	s_waitcnt lgkmcnt(2)
	v_cvt_pk_bf16_f32 v2, v66, v68
	s_waitcnt lgkmcnt(0)
	v_cvt_pk_bf16_f32 v3, v70, v74
	v_lshl_add_u64 v[4:5], v[72:73], 0, v[14:15]
	global_store_dwordx4 v[4:5], v[0:3], off
	v_or_b32_e32 v4, s0, v47
	v_lshlrev_b32_e32 v14, 11, v4
	v_cvt_pk_bf16_f32 v0, v9, v7
	v_cvt_pk_bf16_f32 v1, v11, v39
	v_cvt_pk_bf16_f32 v2, v67, v69
	v_cvt_pk_bf16_f32 v3, v71, v75
	v_lshl_add_u64 v[4:5], v[72:73], 0, v[14:15]
	global_store_dwordx4 v[4:5], v[0:3], off
	s_waitcnt lgkmcnt(0)

.LBB0_41:
	s_andn2_b64 vcc, exec, s[0:1]
	s_cbranch_vccnz .LBB0_59
	s_add_i32 s0, s47, 0xee80
	s_and_b32 s1, s0, 0xffff
	s_mul_i32 s1, s1, 0xba2f
	s_lshr_b32 s1, s1, 23
	s_mul_i32 s4, s1, 0xb0
	s_sub_i32 s0, s0, s4
	s_and_b32 s28, s0, 0xffff
	s_lshl_b32 s5, s1, 6
	s_bfe_i32 s0, s0, 0x10002
	s_lshl_b32 s1, s28, 4
	s_lshl_b32 s4, s28, 5
	s_and_b32 s0, s0, 0xb00
	s_and_b32 s1, s1, 0xf80
	s_add_i32 s0, s0, s1
	s_and_b32 s1, s4, 0x60
	s_or_b32 s0, s0, s1
	v_or_b32_e32 v0, s0, v41
	s_mov_b64 s[0:1], s[50:51]
	v_readlane_b32 s48, v250, 5
	v_lshlrev_b32_e32 v14, 2, v0
	v_readlane_b32 s49, v250, 6
	v_readlane_b32 s50, v250, 7
	v_readlane_b32 s51, v250, 8
	v_lshl_add_u64 v[8:9], s[48:49], 0, v[14:15]
	v_or_b32_e32 v4, s5, v12
	s_mov_b64 s[50:51], s[0:1]
	v_mad_u64_u32 v[0:1], s[0:1], v4, s44, v[8:9]
	global_load_dwordx4 v[108:111], v[0:1], off nt
	v_readlane_b32 s52, v250, 9
	v_readlane_b32 s53, v250, 10
	v_readlane_b32 s54, v250, 11
	v_readlane_b32 s55, v250, 12
	v_or_b32_e32 v174, s5, v43
	v_mad_u64_u32 v[174:175], s[30:31], v174, s44, v[8:9]
	global_load_dwordx4 v[112:115], v[174:175], off nt
	v_or_b32_e32 v176, s5, v45
	v_mad_u64_u32 v[176:177], s[30:31], v176, s44, v[8:9]
	global_load_dwordx4 v[116:119], v[176:177], off nt
	v_or_b32_e32 v178, s5, v47
	v_mad_u64_u32 v[178:179], s[30:31], v178, s44, v[8:9]
	global_load_dwordx4 v[120:123], v[178:179], off nt
	v_or_b32_e32 v180, s5, v48
	v_mad_u64_u32 v[180:181], s[30:31], v180, s44, v[8:9]
	global_load_dwordx4 v[124:127], v[180:181], off nt
	v_or_b32_e32 v182, s5, v49
	v_mad_u64_u32 v[182:183], s[30:31], v182, s44, v[8:9]
	global_load_dwordx4 v[128:131], v[182:183], off nt
	v_or_b32_e32 v184, s5, v50
	v_mad_u64_u32 v[184:185], s[30:31], v184, s44, v[8:9]
	global_load_dwordx4 v[132:135], v[184:185], off nt
	v_or_b32_e32 v186, s5, v51
	v_mad_u64_u32 v[186:187], s[30:31], v186, s44, v[8:9]
	global_load_dwordx4 v[136:139], v[186:187], off nt
	s_andn2_b64 vcc, exec, s[50:51]
	s_cbranch_vccnz .Ltr_d_nogain
	v_add_lshl_u32 v10, v12, s5, 2
	global_load_dword v140, v10, s[62:63]
	global_load_dword v142, v10, s[62:63] offset:32
	global_load_dword v144, v10, s[62:63] offset:64
	global_load_dword v146, v10, s[62:63] offset:96
	global_load_dword v148, v10, s[62:63] offset:128
	global_load_dword v150, v10, s[62:63] offset:160
	global_load_dword v152, v10, s[62:63] offset:192
	global_load_dword v154, v10, s[62:63] offset:224
	s_waitcnt vmcnt(0)
	v_pk_mul_f32 v[108:109], v[108:109], v[140:141] op_sel_hi:[1,0]
	v_pk_mul_f32 v[110:111], v[110:111], v[140:141] op_sel_hi:[1,0]
	v_pk_mul_f32 v[112:113], v[112:113], v[142:143] op_sel_hi:[1,0]
	v_pk_mul_f32 v[114:115], v[114:115], v[142:143] op_sel_hi:[1,0]
	v_pk_mul_f32 v[116:117], v[116:117], v[144:145] op_sel_hi:[1,0]
	v_pk_mul_f32 v[118:119], v[118:119], v[144:145] op_sel_hi:[1,0]
	v_pk_mul_f32 v[120:121], v[120:121], v[146:147] op_sel_hi:[1,0]
	v_pk_mul_f32 v[122:123], v[122:123], v[146:147] op_sel_hi:[1,0]
	v_pk_mul_f32 v[124:125], v[124:125], v[148:149] op_sel_hi:[1,0]
	v_pk_mul_f32 v[126:127], v[126:127], v[148:149] op_sel_hi:[1,0]
	v_pk_mul_f32 v[128:129], v[128:129], v[150:151] op_sel_hi:[1,0]
	v_pk_mul_f32 v[130:131], v[130:131], v[150:151] op_sel_hi:[1,0]
	v_pk_mul_f32 v[132:133], v[132:133], v[152:153] op_sel_hi:[1,0]
	v_pk_mul_f32 v[134:135], v[134:135], v[152:153] op_sel_hi:[1,0]
	v_pk_mul_f32 v[136:137], v[136:137], v[154:155] op_sel_hi:[1,0]
	v_pk_mul_f32 v[138:139], v[138:139], v[154:155] op_sel_hi:[1,0]

.LBB0_60:
	s_andn2_b64 vcc, exec, s[0:1]
	s_cbranch_vccnz .LBB0_62
	s_and_b32 s0, s38, 0x1e0
	s_and_b32 s1, s42, 0x3c0
	v_or_b32_e32 v0, s0, v41
	v_lshlrev_b32_e32 v14, 2, v0
	v_bitop3_b32 v0, s1, v12, v64 bitop3:0xde
	v_lshl_add_u64 v[38:39], s[94:95], 0, v[14:15]
	v_lshlrev_b32_e32 v14, 11, v0
	v_bitop3_b32 v2, s1, v43, v64 bitop3:0xde
	v_lshl_add_u64 v[0:1], v[38:39], 0, v[14:15]
	v_lshlrev_b32_e32 v14, 11, v2
	v_bitop3_b32 v8, s1, v45, v64 bitop3:0xde
	v_lshl_add_u64 v[4:5], v[38:39], 0, v[14:15]
	v_lshlrev_b32_e32 v14, 11, v8
	v_bitop3_b32 v10, s1, v47, v64 bitop3:0xde
	v_lshl_add_u64 v[8:9], v[38:39], 0, v[14:15]
	v_lshlrev_b32_e32 v14, 11, v10
	v_lshl_add_u64 v[66:67], v[38:39], 0, v[14:15]
	v_bitop3_b32 v14, s1, v48, v64 bitop3:0xde
	v_lshlrev_b32_e32 v14, 11, v14
	v_lshl_add_u64 v[70:71], v[38:39], 0, v[14:15]
	v_bitop3_b32 v14, s1, v49, v64 bitop3:0xde
	v_lshlrev_b32_e32 v14, 11, v14
	v_lshl_add_u64 v[74:75], v[38:39], 0, v[14:15]
	global_load_dwordx4 v[0:3], v[0:1], off nt
	s_nop 0
	global_load_dwordx4 v[4:7], v[4:5], off nt
	s_nop 0
	global_load_dwordx4 v[8:11], v[8:9], off nt
	s_nop 0
	global_load_dwordx4 v[66:69], v[66:67], off nt
	s_nop 0
	global_load_dwordx4 v[70:73], v[70:71], off nt
	s_nop 0
	global_load_dwordx4 v[74:77], v[74:75], off nt
	v_bitop3_b32 v14, s1, v50, v64 bitop3:0xde
	v_lshlrev_b32_e32 v14, 11, v14
	v_lshl_add_u64 v[78:79], v[38:39], 0, v[14:15]
	v_bitop3_b32 v14, s1, v51, v64 bitop3:0xde
	global_load_dwordx4 v[78:81], v[78:79], off nt
	v_lshlrev_b32_e32 v14, 11, v14
	v_lshl_add_u64 v[38:39], v[38:39], 0, v[14:15]
	global_load_dwordx4 v[82:85], v[38:39], off nt
	v_add_u32_e32 v65, 0x18c0, v53
	v_add_u32_e32 v92, 0x18c8, v53
	v_add_u32_e32 v93, 0x1ce0, v53
	v_add_u32_e32 v94, 0x1ce8, v53
	s_xor_b32 s1, s1, 0x200
	v_or_b32_e32 v14, s0, v12
	s_lshl_b32 s28, s1, 1
	v_or_b32_e32 v88, s0, v43
	v_lshl_add_u64 v[38:39], v[24:25], 0, s[28:29]
	v_lshlrev_b32_e32 v14, 11, v14
	v_or_b32_e32 v90, s0, v45
	v_lshl_add_u64 v[86:87], v[38:39], 0, v[14:15]
	v_lshlrev_b32_e32 v14, 11, v88
	v_lshl_add_u64 v[88:89], v[38:39], 0, v[14:15]
	v_lshlrev_b32_e32 v14, 11, v90
	v_lshl_add_u64 v[90:91], v[38:39], 0, v[14:15]
	s_waitcnt vmcnt(7)
	ds_write2_b32 v53, v0, v1 offset1:1
	ds_write2_b32 v53, v2, v3 offset0:2 offset1:3
	s_waitcnt vmcnt(6)
	ds_write2_b32 v54, v4, v5 offset1:1
	ds_write2_b32 v55, v6, v7 offset1:1
	s_waitcnt vmcnt(5)
	ds_write2_b32 v56, v8, v9 offset1:1
	ds_write2_b32 v57, v10, v11 offset1:1
	s_waitcnt vmcnt(4)
	ds_write2_b32 v58, v66, v67 offset1:1
	ds_write2_b32 v59, v68, v69 offset1:1
	s_waitcnt vmcnt(3)
	ds_write2_b32 v60, v70, v71 offset1:1
	ds_write2_b32 v61, v72, v73 offset1:1
	s_waitcnt vmcnt(2)
	ds_write2_b32 v62, v74, v75 offset1:1
	ds_write2_b32 v63, v76, v77 offset1:1
	s_waitcnt vmcnt(1)
	ds_write2_b32 v65, v78, v79 offset1:1
	ds_write2_b32 v92, v80, v81 offset1:1
	s_waitcnt vmcnt(0)
	ds_write2_b32 v93, v82, v83 offset1:1
	ds_write2_b32 v94, v84, v85 offset1:1
	s_waitcnt lgkmcnt(0)
	ds_read2_b32 v[4:5], v52 offset0:33 offset1:41
	ds_read2_b32 v[6:7], v52 offset1:8
	ds_read2_b32 v[8:9], v52 offset0:66 offset1:74
	ds_read2_b32 v[10:11], v52 offset0:99 offset1:107
	ds_read2_b32 v[66:67], v52 offset0:132 offset1:140
	ds_read2_b32 v[68:69], v52 offset0:165 offset1:173
	ds_read2_b32 v[70:71], v52 offset0:198 offset1:206
	ds_read2_b32 v[72:73], v52 offset0:231 offset1:239
	ds_read2_b32 v[74:75], v52 offset0:49 offset1:57
	ds_read2_b32 v[76:77], v52 offset0:16 offset1:24
	ds_read2_b32 v[78:79], v52 offset0:82 offset1:90
	ds_read2_b32 v[80:81], v52 offset0:115 offset1:123
	ds_read2_b32 v[82:83], v52 offset0:148 offset1:156
	ds_read2_b32 v[84:85], v52 offset0:181 offset1:189
	ds_read2_b32 v[92:93], v52 offset0:214 offset1:222
	ds_read2_b32 v[94:95], v52 offset0:247 offset1:255
	s_waitcnt lgkmcnt(14)
	v_cvt_pk_bf16_f32 v0, v6, v4
	s_waitcnt lgkmcnt(12)
	v_cvt_pk_bf16_f32 v1, v8, v10
	s_waitcnt lgkmcnt(10)
	v_cvt_pk_bf16_f32 v2, v66, v68
	s_waitcnt lgkmcnt(8)
	v_cvt_pk_bf16_f32 v3, v70, v72
	v_cvt_pk_bf16_f32 v4, v7, v5
	v_cvt_pk_bf16_f32 v5, v9, v11
	v_cvt_pk_bf16_f32 v6, v67, v69
	v_cvt_pk_bf16_f32 v7, v71, v73
	s_waitcnt lgkmcnt(6)
	v_cvt_pk_bf16_f32 v8, v76, v74
	s_waitcnt lgkmcnt(4)
	v_cvt_pk_bf16_f32 v9, v78, v80
	s_waitcnt lgkmcnt(2)
	v_cvt_pk_bf16_f32 v10, v82, v84
	s_waitcnt lgkmcnt(0)
	v_cvt_pk_bf16_f32 v11, v92, v94
	global_store_dwordx4 v[86:87], v[0:3], off
	global_store_dwordx4 v[88:89], v[4:7], off
	global_store_dwordx4 v[90:91], v[8:11], off
	v_cvt_pk_bf16_f32 v0, v77, v75
	v_or_b32_e32 v4, s0, v47
	v_lshlrev_b32_e32 v14, 11, v4
	v_cvt_pk_bf16_f32 v1, v79, v81
	v_cvt_pk_bf16_f32 v2, v83, v85
	v_cvt_pk_bf16_f32 v3, v93, v95
	v_lshl_add_u64 v[4:5], v[38:39], 0, v[14:15]
	global_store_dwordx4 v[4:5], v[0:3], off
	s_waitcnt lgkmcnt(0)

.LBB0_63:
	s_andn2_b64 vcc, exec, s[0:1]
	s_cbranch_vccnz .LBB0_65
	s_and_b32 s0, s38, 0x1e0
	s_and_b32 s1, s42, 0x3c0
	v_or_b32_e32 v0, s0, v41
	v_readlane_b32 s8, v250, 13
	v_lshlrev_b32_e32 v14, 2, v0
	v_readlane_b32 s22, v250, 27
	v_readlane_b32 s23, v250, 28
	v_bitop3_b32 v0, s1, v12, v64 bitop3:0xde
	v_bitop3_b32 v2, s1, v43, v64 bitop3:0xde
	v_lshl_add_u64 v[38:39], s[22:23], 0, v[14:15]
	v_lshlrev_b32_e32 v14, 11, v0
	v_lshl_add_u64 v[0:1], v[38:39], 0, v[14:15]
	v_lshlrev_b32_e32 v14, 11, v2
	v_bitop3_b32 v8, s1, v45, v64 bitop3:0xde
	v_lshl_add_u64 v[4:5], v[38:39], 0, v[14:15]
	v_lshlrev_b32_e32 v14, 11, v8
	v_bitop3_b32 v10, s1, v47, v64 bitop3:0xde
	v_lshl_add_u64 v[8:9], v[38:39], 0, v[14:15]
	v_lshlrev_b32_e32 v14, 11, v10
	v_lshl_add_u64 v[66:67], v[38:39], 0, v[14:15]
	v_bitop3_b32 v14, s1, v48, v64 bitop3:0xde
	v_lshlrev_b32_e32 v14, 11, v14
	v_lshl_add_u64 v[70:71], v[38:39], 0, v[14:15]
	v_bitop3_b32 v14, s1, v49, v64 bitop3:0xde
	v_lshlrev_b32_e32 v14, 11, v14
	v_lshl_add_u64 v[74:75], v[38:39], 0, v[14:15]
	global_load_dwordx4 v[0:3], v[0:1], off nt
	s_nop 0
	global_load_dwordx4 v[4:7], v[4:5], off nt
	s_nop 0
	global_load_dwordx4 v[8:11], v[8:9], off nt
	s_nop 0
	global_load_dwordx4 v[66:69], v[66:67], off nt
	s_nop 0
	global_load_dwordx4 v[70:73], v[70:71], off nt
	s_nop 0
	global_load_dwordx4 v[74:77], v[74:75], off nt
	v_bitop3_b32 v14, s1, v50, v64 bitop3:0xde
	v_lshlrev_b32_e32 v14, 11, v14
	v_lshl_add_u64 v[78:79], v[38:39], 0, v[14:15]
	v_bitop3_b32 v14, s1, v51, v64 bitop3:0xde
	global_load_dwordx4 v[78:81], v[78:79], off nt
	v_lshlrev_b32_e32 v14, 11, v14
	v_lshl_add_u64 v[38:39], v[38:39], 0, v[14:15]
	global_load_dwordx4 v[82:85], v[38:39], off nt
	v_add_u32_e32 v65, 0x18c0, v53
	v_add_u32_e32 v92, 0x18c8, v53
	v_add_u32_e32 v93, 0x1ce0, v53
	v_add_u32_e32 v94, 0x1ce8, v53
	s_xor_b32 s1, s1, 0x200
	v_or_b32_e32 v14, s0, v12
	s_lshl_b32 s28, s1, 1
	v_or_b32_e32 v88, s0, v43
	v_lshl_add_u64 v[38:39], v[26:27], 0, s[28:29]
	v_lshlrev_b32_e32 v14, 11, v14
	v_or_b32_e32 v90, s0, v45
	v_lshl_add_u64 v[86:87], v[38:39], 0, v[14:15]
	v_lshlrev_b32_e32 v14, 11, v88
	v_lshl_add_u64 v[88:89], v[38:39], 0, v[14:15]
	v_lshlrev_b32_e32 v14, 11, v90
	v_lshl_add_u64 v[90:91], v[38:39], 0, v[14:15]
	v_readlane_b32 s9, v250, 14
	v_readlane_b32 s10, v250, 15
	v_readlane_b32 s11, v250, 16
	v_readlane_b32 s12, v250, 17
	v_readlane_b32 s13, v250, 18
	v_readlane_b32 s14, v250, 19
	v_readlane_b32 s15, v250, 20
	v_readlane_b32 s16, v250, 21
	v_readlane_b32 s17, v250, 22
	v_readlane_b32 s18, v250, 23
	v_readlane_b32 s19, v250, 24
	v_readlane_b32 s20, v250, 25
	v_readlane_b32 s21, v250, 26
	s_waitcnt vmcnt(7)
	ds_write2_b32 v53, v0, v1 offset1:1
	ds_write2_b32 v53, v2, v3 offset0:2 offset1:3
	s_waitcnt vmcnt(6)
	ds_write2_b32 v54, v4, v5 offset1:1
	ds_write2_b32 v55, v6, v7 offset1:1
	s_waitcnt vmcnt(5)
	ds_write2_b32 v56, v8, v9 offset1:1
	ds_write2_b32 v57, v10, v11 offset1:1
	s_waitcnt vmcnt(4)
	ds_write2_b32 v58, v66, v67 offset1:1
	ds_write2_b32 v59, v68, v69 offset1:1
	s_waitcnt vmcnt(3)
	ds_write2_b32 v60, v70, v71 offset1:1
	ds_write2_b32 v61, v72, v73 offset1:1
	s_waitcnt vmcnt(2)
	ds_write2_b32 v62, v74, v75 offset1:1
	ds_write2_b32 v63, v76, v77 offset1:1
	s_waitcnt vmcnt(1)
	ds_write2_b32 v65, v78, v79 offset1:1
	ds_write2_b32 v92, v80, v81 offset1:1
	s_waitcnt vmcnt(0)
	ds_write2_b32 v93, v82, v83 offset1:1
	ds_write2_b32 v94, v84, v85 offset1:1
	s_waitcnt lgkmcnt(0)
	ds_read2_b32 v[4:5], v52 offset0:33 offset1:41
	ds_read2_b32 v[6:7], v52 offset1:8
	ds_read2_b32 v[8:9], v52 offset0:66 offset1:74
	ds_read2_b32 v[10:11], v52 offset0:99 offset1:107
	ds_read2_b32 v[66:67], v52 offset0:132 offset1:140
	ds_read2_b32 v[68:69], v52 offset0:165 offset1:173
	ds_read2_b32 v[70:71], v52 offset0:198 offset1:206
	ds_read2_b32 v[72:73], v52 offset0:231 offset1:239
	ds_read2_b32 v[74:75], v52 offset0:49 offset1:57
	ds_read2_b32 v[76:77], v52 offset0:16 offset1:24
	ds_read2_b32 v[78:79], v52 offset0:82 offset1:90
	ds_read2_b32 v[80:81], v52 offset0:115 offset1:123
	ds_read2_b32 v[82:83], v52 offset0:148 offset1:156
	ds_read2_b32 v[84:85], v52 offset0:181 offset1:189
	ds_read2_b32 v[92:93], v52 offset0:214 offset1:222
	ds_read2_b32 v[94:95], v52 offset0:247 offset1:255
	s_waitcnt lgkmcnt(14)
	v_cvt_pk_bf16_f32 v0, v6, v4
	s_waitcnt lgkmcnt(12)
	v_cvt_pk_bf16_f32 v1, v8, v10
	s_waitcnt lgkmcnt(10)
	v_cvt_pk_bf16_f32 v2, v66, v68
	s_waitcnt lgkmcnt(8)
	v_cvt_pk_bf16_f32 v3, v70, v72
	v_cvt_pk_bf16_f32 v4, v7, v5
	v_cvt_pk_bf16_f32 v5, v9, v11
	v_cvt_pk_bf16_f32 v6, v67, v69
	v_cvt_pk_bf16_f32 v7, v71, v73
	s_waitcnt lgkmcnt(6)
	v_cvt_pk_bf16_f32 v8, v76, v74
	s_waitcnt lgkmcnt(4)
	v_cvt_pk_bf16_f32 v9, v78, v80
	s_waitcnt lgkmcnt(2)
	v_cvt_pk_bf16_f32 v10, v82, v84
	s_waitcnt lgkmcnt(0)
	v_cvt_pk_bf16_f32 v11, v92, v94
	global_store_dwordx4 v[86:87], v[0:3], off
	global_store_dwordx4 v[88:89], v[4:7], off
	global_store_dwordx4 v[90:91], v[8:11], off
	v_cvt_pk_bf16_f32 v0, v77, v75
	v_or_b32_e32 v4, s0, v47
	v_lshlrev_b32_e32 v14, 11, v4
	v_cvt_pk_bf16_f32 v1, v79, v81
	v_cvt_pk_bf16_f32 v2, v83, v85
	v_cvt_pk_bf16_f32 v3, v93, v95
	v_lshl_add_u64 v[4:5], v[38:39], 0, v[14:15]
	global_store_dwordx4 v[4:5], v[0:3], off
	s_waitcnt lgkmcnt(0)

.LBB0_66:
	s_andn2_b64 vcc, exec, s[0:1]
	s_cbranch_vccnz .LBB0_68
	s_add_i32 s0, s40, 0x3f00
	s_and_b32 s1, s0, 0x1ffc0
	s_and_b32 s0, s38, 0x3e0
	v_or_b32_e32 v0, s0, v41
	v_readlane_b32 s8, v250, 13
	v_lshlrev_b32_e32 v14, 2, v0
	v_readlane_b32 s20, v250, 25
	v_readlane_b32 s21, v250, 26
	v_or_b32_e32 v0, s1, v12
	v_or_b32_e32 v2, s1, v43
	v_lshl_add_u64 v[38:39], s[20:21], 0, v[14:15]
	v_lshlrev_b32_e32 v14, 12, v0
	v_lshl_add_u64 v[0:1], v[38:39], 0, v[14:15]
	v_lshlrev_b32_e32 v14, 12, v2
	v_or_b32_e32 v8, s1, v45
	v_lshl_add_u64 v[4:5], v[38:39], 0, v[14:15]
	v_lshlrev_b32_e32 v14, 12, v8
	v_or_b32_e32 v10, s1, v47
	v_lshl_add_u64 v[8:9], v[38:39], 0, v[14:15]
	v_lshlrev_b32_e32 v14, 12, v10
	v_lshl_add_u64 v[66:67], v[38:39], 0, v[14:15]
	v_or_b32_e32 v14, s1, v48
	v_lshlrev_b32_e32 v14, 12, v14
	v_lshl_add_u64 v[70:71], v[38:39], 0, v[14:15]
	v_or_b32_e32 v14, s1, v49
	v_lshlrev_b32_e32 v14, 12, v14
	v_lshl_add_u64 v[74:75], v[38:39], 0, v[14:15]
	global_load_dwordx4 v[0:3], v[0:1], off nt
	s_nop 0
	global_load_dwordx4 v[4:7], v[4:5], off nt
	s_nop 0
	global_load_dwordx4 v[8:11], v[8:9], off nt
	s_nop 0
	global_load_dwordx4 v[66:69], v[66:67], off nt
	s_nop 0
	global_load_dwordx4 v[70:73], v[70:71], off nt
	s_nop 0
	global_load_dwordx4 v[74:77], v[74:75], off nt
	v_or_b32_e32 v14, s1, v50
	v_lshlrev_b32_e32 v14, 12, v14
	v_lshl_add_u64 v[78:79], v[38:39], 0, v[14:15]
	v_or_b32_e32 v14, s1, v51
	global_load_dwordx4 v[78:81], v[78:79], off nt
	v_lshlrev_b32_e32 v14, 12, v14
	v_lshl_add_u64 v[38:39], v[38:39], 0, v[14:15]
	global_load_dwordx4 v[82:85], v[38:39], off nt
	v_add_u32_e32 v65, 0x18c0, v53
	v_add_u32_e32 v92, 0x18c8, v53
	v_add_u32_e32 v93, 0x1ce0, v53
	v_add_u32_e32 v94, 0x1ce8, v53
	v_or_b32_e32 v14, s0, v12
	s_lshl_b32 s28, s1, 1
	v_or_b32_e32 v88, s0, v43
	v_lshl_add_u64 v[38:39], v[28:29], 0, s[28:29]
	v_lshlrev_b32_e32 v14, 11, v14
	v_or_b32_e32 v90, s0, v45
	v_lshl_add_u64 v[86:87], v[38:39], 0, v[14:15]
	v_lshlrev_b32_e32 v14, 11, v88
	v_lshl_add_u64 v[88:89], v[38:39], 0, v[14:15]
	v_lshlrev_b32_e32 v14, 11, v90
	v_lshl_add_u64 v[90:91], v[38:39], 0, v[14:15]
	v_readlane_b32 s9, v250, 14
	v_readlane_b32 s10, v250, 15
	v_readlane_b32 s11, v250, 16
	v_readlane_b32 s12, v250, 17
	v_readlane_b32 s13, v250, 18
	v_readlane_b32 s14, v250, 19
	v_readlane_b32 s15, v250, 20
	v_readlane_b32 s16, v250, 21
	v_readlane_b32 s17, v250, 22
	v_readlane_b32 s18, v250, 23
	v_readlane_b32 s19, v250, 24
	v_readlane_b32 s22, v250, 27
	v_readlane_b32 s23, v250, 28
	s_waitcnt vmcnt(7)
	ds_write2_b32 v53, v0, v1 offset1:1
	ds_write2_b32 v53, v2, v3 offset0:2 offset1:3
	s_waitcnt vmcnt(6)
	ds_write2_b32 v54, v4, v5 offset1:1
	ds_write2_b32 v55, v6, v7 offset1:1
	s_waitcnt vmcnt(5)
	ds_write2_b32 v56, v8, v9 offset1:1
	ds_write2_b32 v57, v10, v11 offset1:1
	s_waitcnt vmcnt(4)
	ds_write2_b32 v58, v66, v67 offset1:1
	ds_write2_b32 v59, v68, v69 offset1:1
	s_waitcnt vmcnt(3)
	ds_write2_b32 v60, v70, v71 offset1:1
	ds_write2_b32 v61, v72, v73 offset1:1
	s_waitcnt vmcnt(2)
	ds_write2_b32 v62, v74, v75 offset1:1
	ds_write2_b32 v63, v76, v77 offset1:1
	s_waitcnt vmcnt(1)
	ds_write2_b32 v65, v78, v79 offset1:1
	ds_write2_b32 v92, v80, v81 offset1:1
	s_waitcnt vmcnt(0)
	ds_write2_b32 v93, v82, v83 offset1:1
	ds_write2_b32 v94, v84, v85 offset1:1
	s_waitcnt lgkmcnt(0)
	ds_read2_b32 v[4:5], v52 offset0:33 offset1:41
	ds_read2_b32 v[6:7], v52 offset1:8
	ds_read2_b32 v[8:9], v52 offset0:66 offset1:74
	ds_read2_b32 v[10:11], v52 offset0:99 offset1:107
	ds_read2_b32 v[66:67], v52 offset0:132 offset1:140
	ds_read2_b32 v[68:69], v52 offset0:165 offset1:173
	ds_read2_b32 v[70:71], v52 offset0:198 offset1:206
	ds_read2_b32 v[72:73], v52 offset0:231 offset1:239
	ds_read2_b32 v[74:75], v52 offset0:49 offset1:57
	ds_read2_b32 v[76:77], v52 offset0:16 offset1:24
	ds_read2_b32 v[78:79], v52 offset0:82 offset1:90
	ds_read2_b32 v[80:81], v52 offset0:115 offset1:123
	ds_read2_b32 v[82:83], v52 offset0:148 offset1:156
	ds_read2_b32 v[84:85], v52 offset0:181 offset1:189
	ds_read2_b32 v[92:93], v52 offset0:214 offset1:222
	ds_read2_b32 v[94:95], v52 offset0:247 offset1:255
	s_waitcnt lgkmcnt(14)
	v_cvt_pk_bf16_f32 v0, v6, v4
	s_waitcnt lgkmcnt(12)
	v_cvt_pk_bf16_f32 v1, v8, v10
	s_waitcnt lgkmcnt(10)
	v_cvt_pk_bf16_f32 v2, v66, v68
	s_waitcnt lgkmcnt(8)
	v_cvt_pk_bf16_f32 v3, v70, v72
	v_cvt_pk_bf16_f32 v4, v7, v5
	v_cvt_pk_bf16_f32 v5, v9, v11
	v_cvt_pk_bf16_f32 v6, v67, v69
	v_cvt_pk_bf16_f32 v7, v71, v73
	s_waitcnt lgkmcnt(6)
	v_cvt_pk_bf16_f32 v8, v76, v74
	s_waitcnt lgkmcnt(4)
	v_cvt_pk_bf16_f32 v9, v78, v80
	s_waitcnt lgkmcnt(2)
	v_cvt_pk_bf16_f32 v10, v82, v84
	s_waitcnt lgkmcnt(0)
	v_cvt_pk_bf16_f32 v11, v92, v94
	global_store_dwordx4 v[86:87], v[0:3], off
	global_store_dwordx4 v[88:89], v[4:7], off
	global_store_dwordx4 v[90:91], v[8:11], off
	v_cvt_pk_bf16_f32 v0, v77, v75
	v_or_b32_e32 v4, s0, v47
	v_lshlrev_b32_e32 v14, 11, v4
	v_cvt_pk_bf16_f32 v1, v79, v81
	v_cvt_pk_bf16_f32 v2, v83, v85
	v_cvt_pk_bf16_f32 v3, v93, v95
	v_lshl_add_u64 v[4:5], v[38:39], 0, v[14:15]
	global_store_dwordx4 v[4:5], v[0:3], off
	s_waitcnt lgkmcnt(0)

.LBB0_69:
	s_andn2_b64 vcc, exec, s[0:1]
	s_cbranch_vccnz .LBB0_88
	s_add_i32 s0, s47, 0xf580
	s_and_b32 s1, s0, 0xffff
	s_mul_i32 s1, s1, 0xaaab
	s_lshr_b32 s1, s1, 21
	s_mul_i32 s4, s1, 48
	s_sub_i32 s0, s0, s4
	s_lshl_b32 s0, s0, 5
	s_and_b32 s4, s0, 0xffe0
	v_or_b32_e32 v0, s4, v41
	v_readlane_b32 s8, v250, 13
	s_lshl_b32 s5, s1, 6
	v_lshlrev_b32_e32 v14, 2, v0
	v_readlane_b32 s14, v250, 19
	v_readlane_b32 s15, v250, 20
	v_or_b32_e32 v0, s5, v12
	v_cndmask_b32_e64 v1, 0, 1, s[96:97]
	v_lshl_add_u64 v[38:39], s[14:15], 0, v[14:15]
	v_mad_u64_u32 v[2:3], s[0:1], v0, s45, v[38:39]
	global_load_dwordx4 v[108:111], v[2:3], off nt
	v_readlane_b32 s12, v250, 17
	v_readlane_b32 s13, v250, 18
	v_readlane_b32 s9, v250, 14
	v_readlane_b32 s10, v250, 15
	v_readlane_b32 s11, v250, 16
	v_readlane_b32 s16, v250, 21
	v_readlane_b32 s17, v250, 22
	v_readlane_b32 s18, v250, 23
	v_readlane_b32 s19, v250, 24
	v_readlane_b32 s20, v250, 25
	v_readlane_b32 s21, v250, 26
	v_readlane_b32 s22, v250, 27
	v_readlane_b32 s23, v250, 28
	v_or_b32_e32 v174, s5, v43
	v_mad_u64_u32 v[174:175], s[30:31], v174, s45, v[38:39]
	global_load_dwordx4 v[112:115], v[174:175], off nt
	v_or_b32_e32 v176, s5, v45
	v_mad_u64_u32 v[176:177], s[30:31], v176, s45, v[38:39]
	global_load_dwordx4 v[116:119], v[176:177], off nt
	v_or_b32_e32 v178, s5, v47
	v_mad_u64_u32 v[178:179], s[30:31], v178, s45, v[38:39]
	global_load_dwordx4 v[120:123], v[178:179], off nt
	v_or_b32_e32 v180, s5, v48
	v_mad_u64_u32 v[180:181], s[30:31], v180, s45, v[38:39]
	global_load_dwordx4 v[124:127], v[180:181], off nt
	v_or_b32_e32 v182, s5, v49
	v_mad_u64_u32 v[182:183], s[30:31], v182, s45, v[38:39]
	global_load_dwordx4 v[128:131], v[182:183], off nt
	v_or_b32_e32 v184, s5, v50
	v_mad_u64_u32 v[184:185], s[30:31], v184, s45, v[38:39]
	global_load_dwordx4 v[132:135], v[184:185], off nt
	v_or_b32_e32 v186, s5, v51
	v_mad_u64_u32 v[186:187], s[30:31], v186, s45, v[38:39]
	global_load_dwordx4 v[136:139], v[186:187], off nt
	s_mov_b32 s30, s82
	s_andn2_b64 vcc, exec, s[96:97]
	s_cbranch_vccnz .Ltr_h_nogain
	v_add_lshl_u32 v14, s5, v12, 2
	global_load_dword v140, v14, s[12:13]
	global_load_dword v142, v14, s[12:13] offset:32
	global_load_dword v144, v14, s[12:13] offset:64
	global_load_dword v146, v14, s[12:13] offset:96
	global_load_dword v148, v14, s[12:13] offset:128
	global_load_dword v150, v14, s[12:13] offset:160
	global_load_dword v152, v14, s[12:13] offset:192
	global_load_dword v154, v14, s[12:13] offset:224
	s_waitcnt vmcnt(0)
	v_pk_mul_f32 v[108:109], v[108:109], v[140:141] op_sel_hi:[1,0]
	v_pk_mul_f32 v[110:111], v[110:111], v[140:141] op_sel_hi:[1,0]
	v_pk_mul_f32 v[112:113], v[112:113], v[142:143] op_sel_hi:[1,0]
	v_pk_mul_f32 v[114:115], v[114:115], v[142:143] op_sel_hi:[1,0]
	v_pk_mul_f32 v[116:117], v[116:117], v[144:145] op_sel_hi:[1,0]
	v_pk_mul_f32 v[118:119], v[118:119], v[144:145] op_sel_hi:[1,0]
	v_pk_mul_f32 v[120:121], v[120:121], v[146:147] op_sel_hi:[1,0]
	v_pk_mul_f32 v[122:123], v[122:123], v[146:147] op_sel_hi:[1,0]
	v_pk_mul_f32 v[124:125], v[124:125], v[148:149] op_sel_hi:[1,0]
	v_pk_mul_f32 v[126:127], v[126:127], v[148:149] op_sel_hi:[1,0]
	v_pk_mul_f32 v[128:129], v[128:129], v[150:151] op_sel_hi:[1,0]
	v_pk_mul_f32 v[130:131], v[130:131], v[150:151] op_sel_hi:[1,0]
	v_pk_mul_f32 v[132:133], v[132:133], v[152:153] op_sel_hi:[1,0]
	v_pk_mul_f32 v[134:135], v[134:135], v[152:153] op_sel_hi:[1,0]
	v_pk_mul_f32 v[136:137], v[136:137], v[154:155] op_sel_hi:[1,0]
	v_pk_mul_f32 v[138:139], v[138:139], v[154:155] op_sel_hi:[1,0]

.LBB0_89:
	s_andn2_b64 vcc, exec, s[0:1]
	s_cbranch_vccnz .LBB0_91
	s_add_i32 s0, s40, 0x4900
	s_and_b32 s1, s0, 0x1ffc0
	s_and_b32 s0, s38, 0x3e0
	v_or_b32_e32 v0, s0, v41
	v_readlane_b32 s8, v250, 13
	v_lshlrev_b32_e32 v14, 2, v0
	v_readlane_b32 s16, v250, 21
	v_readlane_b32 s17, v250, 22
	v_or_b32_e32 v4, s1, v12
	v_or_b32_e32 v8, s1, v43
	v_lshl_add_u64 v[38:39], s[16:17], 0, v[14:15]
	v_lshlrev_b32_e32 v14, 12, v4
	v_lshl_add_u64 v[0:1], v[38:39], 0, v[14:15]
	v_lshlrev_b32_e32 v4, 2, v4
	v_lshlrev_b32_e32 v14, 12, v8
	v_lshlrev_b32_e32 v8, 2, v8
	v_or_b32_e32 v65, s1, v45
	global_load_dword v86, v4, s[24:25]
	global_load_dword v88, v8, s[24:25]
	v_lshl_add_u64 v[4:5], v[38:39], 0, v[14:15]
	v_lshlrev_b32_e32 v14, 12, v65
	v_lshl_add_u64 v[8:9], v[38:39], 0, v[14:15]
	v_lshlrev_b32_e32 v14, 2, v65
	v_or_b32_e32 v65, s1, v47
	global_load_dword v90, v14, s[24:25]
	v_lshlrev_b32_e32 v14, 12, v65
	v_lshl_add_u64 v[66:67], v[38:39], 0, v[14:15]
	v_lshlrev_b32_e32 v14, 2, v65
	v_or_b32_e32 v65, s1, v48
	global_load_dword v92, v14, s[24:25]
	v_lshlrev_b32_e32 v14, 12, v65
	global_load_dwordx4 v[0:3], v[0:1], off nt
	v_lshl_add_u64 v[70:71], v[38:39], 0, v[14:15]
	v_lshlrev_b32_e32 v14, 2, v65
	v_or_b32_e32 v65, s1, v49
	global_load_dwordx4 v[4:7], v[4:5], off nt
	v_add_u32_e32 v87, 0x1ce8, v53
	global_load_dword v94, v14, s[24:25]
	v_lshlrev_b32_e32 v14, 12, v65
	global_load_dwordx4 v[8:11], v[8:9], off nt
	v_lshl_add_u64 v[74:75], v[38:39], 0, v[14:15]
	v_lshlrev_b32_e32 v14, 2, v65
	v_or_b32_e32 v65, s1, v50
	global_load_dwordx4 v[66:69], v[66:67], off nt
	s_lshl_b32 s28, s1, 1
	global_load_dword v96, v14, s[24:25]
	v_lshlrev_b32_e32 v14, 12, v65
	global_load_dwordx4 v[70:73], v[70:71], off nt
	v_lshl_add_u64 v[78:79], v[38:39], 0, v[14:15]
	v_lshlrev_b32_e32 v14, 2, v65
	v_or_b32_e32 v65, s1, v51
	global_load_dwordx4 v[74:77], v[74:75], off nt
	v_readlane_b32 s9, v250, 14
	global_load_dword v98, v14, s[24:25]
	v_lshlrev_b32_e32 v14, 12, v65
	global_load_dwordx4 v[78:81], v[78:79], off nt
	v_lshl_add_u64 v[38:39], v[38:39], 0, v[14:15]
	v_lshlrev_b32_e32 v14, 2, v65
	global_load_dword v14, v14, s[24:25]
	s_nop 0
	global_load_dwordx4 v[82:85], v[38:39], off nt
	v_add_u32_e32 v38, 0x18c0, v53
	v_add_u32_e32 v39, 0x18c8, v53
	v_add_u32_e32 v65, 0x1ce0, v53
	v_readlane_b32 s10, v250, 15
	v_readlane_b32 s11, v250, 16
	v_readlane_b32 s12, v250, 17
	v_readlane_b32 s13, v250, 18
	v_readlane_b32 s14, v250, 19
	v_readlane_b32 s15, v250, 20
	v_readlane_b32 s18, v250, 23
	v_readlane_b32 s19, v250, 24
	v_readlane_b32 s20, v250, 25
	v_readlane_b32 s21, v250, 26
	v_readlane_b32 s22, v250, 27
	v_readlane_b32 s23, v250, 28
	s_waitcnt vmcnt(11)
	v_pk_mul_f32 v[2:3], v[2:3], v[86:87] op_sel_hi:[1,0]
	v_pk_mul_f32 v[0:1], v[0:1], v[86:87] op_sel_hi:[1,0]
	ds_write2_b32 v53, v0, v1 offset1:1
	ds_write2_b32 v53, v2, v3 offset0:2 offset1:3
	s_waitcnt vmcnt(10)
	v_pk_mul_f32 v[2:3], v[4:5], v[88:89] op_sel_hi:[1,0]
	v_pk_mul_f32 v[0:1], v[6:7], v[88:89] op_sel_hi:[1,0]
	ds_write2_b32 v54, v2, v3 offset1:1
	ds_write2_b32 v55, v0, v1 offset1:1
	s_waitcnt vmcnt(8)
	v_pk_mul_f32 v[2:3], v[8:9], v[90:91] op_sel_hi:[1,0]
	v_pk_mul_f32 v[0:1], v[10:11], v[90:91] op_sel_hi:[1,0]
	ds_write2_b32 v56, v2, v3 offset1:1
	ds_write2_b32 v57, v0, v1 offset1:1
	s_waitcnt vmcnt(7)
	v_pk_mul_f32 v[2:3], v[66:67], v[92:93] op_sel_hi:[1,0]
	v_pk_mul_f32 v[0:1], v[68:69], v[92:93] op_sel_hi:[1,0]
	ds_write2_b32 v58, v2, v3 offset1:1
	ds_write2_b32 v59, v0, v1 offset1:1
	s_waitcnt vmcnt(5)
	v_pk_mul_f32 v[2:3], v[70:71], v[94:95] op_sel_hi:[1,0]
	v_pk_mul_f32 v[0:1], v[72:73], v[94:95] op_sel_hi:[1,0]
	ds_write2_b32 v60, v2, v3 offset1:1
	ds_write2_b32 v61, v0, v1 offset1:1
	v_lshl_add_u64 v[72:73], v[32:33], 0, s[28:29]
	s_waitcnt vmcnt(4)
	v_pk_mul_f32 v[2:3], v[74:75], v[96:97] op_sel_hi:[1,0]
	v_pk_mul_f32 v[0:1], v[76:77], v[96:97] op_sel_hi:[1,0]
	ds_write2_b32 v62, v2, v3 offset1:1
	ds_write2_b32 v63, v0, v1 offset1:1
	s_waitcnt vmcnt(2)
	v_pk_mul_f32 v[2:3], v[78:79], v[98:99] op_sel_hi:[1,0]
	v_pk_mul_f32 v[0:1], v[80:81], v[98:99] op_sel_hi:[1,0]
	ds_write2_b32 v38, v2, v3 offset1:1
	ds_write2_b32 v39, v0, v1 offset1:1
	s_waitcnt vmcnt(0)
	v_pk_mul_f32 v[2:3], v[82:83], v[14:15] op_sel_hi:[1,0]
	v_pk_mul_f32 v[0:1], v[84:85], v[14:15] op_sel_hi:[1,0]
	ds_write2_b32 v65, v2, v3 offset1:1
	ds_write2_b32 v87, v0, v1 offset1:1
	s_waitcnt lgkmcnt(0)
	ds_read2_b32 v[4:5], v52 offset0:33 offset1:41
	ds_read2_b32 v[6:7], v52 offset1:8
	ds_read2_b32 v[8:9], v52 offset0:66 offset1:74
	ds_read2_b32 v[10:11], v52 offset0:99 offset1:107
	ds_read2_b32 v[38:39], v52 offset0:132 offset1:140
	ds_read2_b32 v[66:67], v52 offset0:165 offset1:173
	ds_read2_b32 v[68:69], v52 offset0:198 offset1:206
	ds_read2_b32 v[70:71], v52 offset0:231 offset1:239
	s_waitcnt lgkmcnt(6)
	v_cvt_pk_bf16_f32 v0, v6, v4
	v_or_b32_e32 v4, s0, v12
	v_lshlrev_b32_e32 v14, 11, v4
	s_waitcnt lgkmcnt(4)
	v_cvt_pk_bf16_f32 v1, v8, v10
	s_waitcnt lgkmcnt(2)
	v_cvt_pk_bf16_f32 v2, v38, v66
	s_waitcnt lgkmcnt(0)
	v_cvt_pk_bf16_f32 v3, v68, v70
	v_lshl_add_u64 v[74:75], v[72:73], 0, v[14:15]
	global_store_dwordx4 v[74:75], v[0:3], off
	v_or_b32_e32 v4, s0, v43
	v_lshlrev_b32_e32 v14, 11, v4
	v_cvt_pk_bf16_f32 v0, v7, v5
	v_cvt_pk_bf16_f32 v1, v9, v11
	v_cvt_pk_bf16_f32 v2, v39, v67
	v_cvt_pk_bf16_f32 v3, v69, v71
	ds_read2_b32 v[6:7], v52 offset0:49 offset1:57
	ds_read2_b32 v[8:9], v52 offset0:16 offset1:24
	ds_read2_b32 v[10:11], v52 offset0:82 offset1:90
	ds_read2_b32 v[38:39], v52 offset0:115 offset1:123
	ds_read2_b32 v[66:67], v52 offset0:148 offset1:156
	ds_read2_b32 v[68:69], v52 offset0:181 offset1:189
	ds_read2_b32 v[70:71], v52 offset0:214 offset1:222
	ds_read2_b32 v[74:75], v52 offset0:247 offset1:255
	v_lshl_add_u64 v[4:5], v[72:73], 0, v[14:15]
	global_store_dwordx4 v[4:5], v[0:3], off
	v_or_b32_e32 v4, s0, v45
	v_lshlrev_b32_e32 v14, 11, v4
	s_waitcnt lgkmcnt(6)
	v_cvt_pk_bf16_f32 v0, v8, v6
	s_waitcnt lgkmcnt(4)
	v_cvt_pk_bf16_f32 v1, v10, v38
	s_waitcnt lgkmcnt(2)
	v_cvt_pk_bf16_f32 v2, v66, v68
	s_waitcnt lgkmcnt(0)
	v_cvt_pk_bf16_f32 v3, v70, v74
	v_lshl_add_u64 v[4:5], v[72:73], 0, v[14:15]
	global_store_dwordx4 v[4:5], v[0:3], off
	v_or_b32_e32 v4, s0, v47
	v_lshlrev_b32_e32 v14, 11, v4
	v_cvt_pk_bf16_f32 v0, v9, v7
	v_cvt_pk_bf16_f32 v1, v11, v39
	v_cvt_pk_bf16_f32 v2, v67, v69
	v_cvt_pk_bf16_f32 v3, v71, v75
	v_lshl_add_u64 v[4:5], v[72:73], 0, v[14:15]
	global_store_dwordx4 v[4:5], v[0:3], off
	s_waitcnt lgkmcnt(0)

.LBB0_92:
	s_andn2_b64 vcc, exec, s[0:1]
	s_cbranch_vccnz .LBB0_94
	s_add_i32 s0, s40, 0x4d00
	s_and_b32 s1, s0, 0x1ffc0
	s_and_b32 s0, s38, 0x3e0
	v_or_b32_e32 v0, s0, v41
	v_readlane_b32 s8, v250, 13
	v_lshlrev_b32_e32 v14, 2, v0
	v_readlane_b32 s10, v250, 15
	v_readlane_b32 s11, v250, 16
	v_or_b32_e32 v0, s1, v12
	v_or_b32_e32 v2, s1, v43
	v_lshl_add_u64 v[38:39], s[10:11], 0, v[14:15]
	v_lshlrev_b32_e32 v14, 12, v0
	v_lshl_add_u64 v[0:1], v[38:39], 0, v[14:15]
	v_lshlrev_b32_e32 v14, 12, v2
	v_or_b32_e32 v8, s1, v45
	v_lshl_add_u64 v[4:5], v[38:39], 0, v[14:15]
	v_lshlrev_b32_e32 v14, 12, v8
	v_or_b32_e32 v10, s1, v47
	v_lshl_add_u64 v[8:9], v[38:39], 0, v[14:15]
	v_lshlrev_b32_e32 v14, 12, v10
	v_lshl_add_u64 v[66:67], v[38:39], 0, v[14:15]
	v_or_b32_e32 v14, s1, v48
	v_lshlrev_b32_e32 v14, 12, v14
	v_lshl_add_u64 v[70:71], v[38:39], 0, v[14:15]
	v_or_b32_e32 v14, s1, v49
	v_lshlrev_b32_e32 v14, 12, v14
	v_lshl_add_u64 v[74:75], v[38:39], 0, v[14:15]
	global_load_dwordx4 v[0:3], v[0:1], off nt
	s_nop 0
	global_load_dwordx4 v[4:7], v[4:5], off nt
	s_nop 0
	global_load_dwordx4 v[8:11], v[8:9], off nt
	s_nop 0
	global_load_dwordx4 v[66:69], v[66:67], off nt
	s_nop 0
	global_load_dwordx4 v[70:73], v[70:71], off nt
	s_nop 0
	global_load_dwordx4 v[74:77], v[74:75], off nt
	v_or_b32_e32 v14, s1, v50
	v_lshlrev_b32_e32 v14, 12, v14
	v_lshl_add_u64 v[78:79], v[38:39], 0, v[14:15]
	v_or_b32_e32 v14, s1, v51
	global_load_dwordx4 v[78:81], v[78:79], off nt
	v_lshlrev_b32_e32 v14, 12, v14
	v_lshl_add_u64 v[38:39], v[38:39], 0, v[14:15]
	global_load_dwordx4 v[82:85], v[38:39], off nt
	v_add_u32_e32 v65, 0x18c0, v53
	v_add_u32_e32 v92, 0x18c8, v53
	v_add_u32_e32 v93, 0x1ce0, v53
	v_add_u32_e32 v94, 0x1ce8, v53
	v_or_b32_e32 v14, s0, v12
	s_lshl_b32 s28, s1, 1
	v_or_b32_e32 v88, s0, v43
	v_lshl_add_u64 v[38:39], v[34:35], 0, s[28:29]
	v_lshlrev_b32_e32 v14, 11, v14
	v_or_b32_e32 v90, s0, v45
	v_lshl_add_u64 v[86:87], v[38:39], 0, v[14:15]
	v_lshlrev_b32_e32 v14, 11, v88
	v_lshl_add_u64 v[88:89], v[38:39], 0, v[14:15]
	v_lshlrev_b32_e32 v14, 11, v90
	v_lshl_add_u64 v[90:91], v[38:39], 0, v[14:15]
	v_readlane_b32 s9, v250, 14
	v_readlane_b32 s12, v250, 17
	v_readlane_b32 s13, v250, 18
	v_readlane_b32 s14, v250, 19
	v_readlane_b32 s15, v250, 20
	v_readlane_b32 s16, v250, 21
	v_readlane_b32 s17, v250, 22
	v_readlane_b32 s18, v250, 23
	v_readlane_b32 s19, v250, 24
	v_readlane_b32 s20, v250, 25
	v_readlane_b32 s21, v250, 26
	v_readlane_b32 s22, v250, 27
	v_readlane_b32 s23, v250, 28
	s_waitcnt vmcnt(7)
	ds_write2_b32 v53, v0, v1 offset1:1
	ds_write2_b32 v53, v2, v3 offset0:2 offset1:3
	s_waitcnt vmcnt(6)
	ds_write2_b32 v54, v4, v5 offset1:1
	ds_write2_b32 v55, v6, v7 offset1:1
	s_waitcnt vmcnt(5)
	ds_write2_b32 v56, v8, v9 offset1:1
	ds_write2_b32 v57, v10, v11 offset1:1
	s_waitcnt vmcnt(4)
	ds_write2_b32 v58, v66, v67 offset1:1
	ds_write2_b32 v59, v68, v69 offset1:1
	s_waitcnt vmcnt(3)
	ds_write2_b32 v60, v70, v71 offset1:1
	ds_write2_b32 v61, v72, v73 offset1:1
	s_waitcnt vmcnt(2)
	ds_write2_b32 v62, v74, v75 offset1:1
	ds_write2_b32 v63, v76, v77 offset1:1
	s_waitcnt vmcnt(1)
	ds_write2_b32 v65, v78, v79 offset1:1
	ds_write2_b32 v92, v80, v81 offset1:1
	s_waitcnt vmcnt(0)
	ds_write2_b32 v93, v82, v83 offset1:1
	ds_write2_b32 v94, v84, v85 offset1:1
	s_waitcnt lgkmcnt(0)
	ds_read2_b32 v[4:5], v52 offset0:33 offset1:41
	ds_read2_b32 v[6:7], v52 offset1:8
	ds_read2_b32 v[8:9], v52 offset0:66 offset1:74
	ds_read2_b32 v[10:11], v52 offset0:99 offset1:107
	ds_read2_b32 v[66:67], v52 offset0:132 offset1:140
	ds_read2_b32 v[68:69], v52 offset0:165 offset1:173
	ds_read2_b32 v[70:71], v52 offset0:198 offset1:206
	ds_read2_b32 v[72:73], v52 offset0:231 offset1:239
	ds_read2_b32 v[74:75], v52 offset0:49 offset1:57
	ds_read2_b32 v[76:77], v52 offset0:16 offset1:24
	ds_read2_b32 v[78:79], v52 offset0:82 offset1:90
	ds_read2_b32 v[80:81], v52 offset0:115 offset1:123
	ds_read2_b32 v[82:83], v52 offset0:148 offset1:156
	ds_read2_b32 v[84:85], v52 offset0:181 offset1:189
	ds_read2_b32 v[92:93], v52 offset0:214 offset1:222
	ds_read2_b32 v[94:95], v52 offset0:247 offset1:255
	s_waitcnt lgkmcnt(14)
	v_cvt_pk_bf16_f32 v0, v6, v4
	s_waitcnt lgkmcnt(12)
	v_cvt_pk_bf16_f32 v1, v8, v10
	s_waitcnt lgkmcnt(10)
	v_cvt_pk_bf16_f32 v2, v66, v68
	s_waitcnt lgkmcnt(8)
	v_cvt_pk_bf16_f32 v3, v70, v72
	v_cvt_pk_bf16_f32 v4, v7, v5
	v_cvt_pk_bf16_f32 v5, v9, v11
	v_cvt_pk_bf16_f32 v6, v67, v69
	v_cvt_pk_bf16_f32 v7, v71, v73
	s_waitcnt lgkmcnt(6)
	v_cvt_pk_bf16_f32 v8, v76, v74
	s_waitcnt lgkmcnt(4)
	v_cvt_pk_bf16_f32 v9, v78, v80
	s_waitcnt lgkmcnt(2)
	v_cvt_pk_bf16_f32 v10, v82, v84
	s_waitcnt lgkmcnt(0)
	v_cvt_pk_bf16_f32 v11, v92, v94
	global_store_dwordx4 v[86:87], v[0:3], off
	global_store_dwordx4 v[88:89], v[4:7], off
	global_store_dwordx4 v[90:91], v[8:11], off
	v_cvt_pk_bf16_f32 v0, v77, v75
	v_or_b32_e32 v4, s0, v47
	v_lshlrev_b32_e32 v14, 11, v4
	v_cvt_pk_bf16_f32 v1, v79, v81
	v_cvt_pk_bf16_f32 v2, v83, v85
	v_cvt_pk_bf16_f32 v3, v93, v95
	v_lshl_add_u64 v[4:5], v[38:39], 0, v[14:15]
	global_store_dwordx4 v[4:5], v[0:3], off
	s_waitcnt lgkmcnt(0)

.LBB0_95:
	s_andn2_b64 vcc, exec, s[0:1]
	s_cbranch_vccnz .LBB0_23
	s_mul_hi_i32 s0, s47, 0x4ec4ec4f
	s_lshr_b32 s1, s0, 31
	s_ashr_i32 s30, s0, 5
	s_add_i32 s30, s30, s1
	s_mul_i32 s28, s30, 0xfffff300
	s_add_i32 s28, s28, s38
	v_add_u32_e32 v0, s28, v41
	s_movk_i32 s0, 0xc00
	v_add_u32_e32 v1, 8, v0
	v_cmp_gt_i32_e32 vcc, s0, v0
	s_nop 1
	v_cndmask_b32_e32 v14, v1, v0, vcc
	s_mov_b64 s[4:5], 0
	s_lshl_b32 s30, s30, 6
	v_lshl_add_u64 v[8:9], v[14:15], 2, s[64:65]
	v_or_b32_e32 v172, s30, v12
	v_mad_i64_i32 v[172:173], s[48:49], v172, s46, v[8:9]
	global_load_dwordx4 v[108:111], v[172:173], off nt
	v_or_b32_e32 v174, s30, v43
	v_mad_i64_i32 v[174:175], s[48:49], v174, s46, v[8:9]
	global_load_dwordx4 v[112:115], v[174:175], off nt
	v_or_b32_e32 v176, s30, v45
	v_mad_i64_i32 v[176:177], s[48:49], v176, s46, v[8:9]
	global_load_dwordx4 v[116:119], v[176:177], off nt
	v_or_b32_e32 v178, s30, v47
	v_mad_i64_i32 v[178:179], s[48:49], v178, s46, v[8:9]
	global_load_dwordx4 v[120:123], v[178:179], off nt
	v_or_b32_e32 v180, s30, v48
	v_mad_i64_i32 v[180:181], s[48:49], v180, s46, v[8:9]
	global_load_dwordx4 v[124:127], v[180:181], off nt
	v_or_b32_e32 v182, s30, v49
	v_mad_i64_i32 v[182:183], s[48:49], v182, s46, v[8:9]
	global_load_dwordx4 v[128:131], v[182:183], off nt
	v_or_b32_e32 v184, s30, v50
	v_mad_i64_i32 v[184:185], s[48:49], v184, s46, v[8:9]
	global_load_dwordx4 v[132:135], v[184:185], off nt
	v_or_b32_e32 v186, s30, v51
	v_mad_i64_i32 v[186:187], s[48:49], v186, s46, v[8:9]
	global_load_dwordx4 v[136:139], v[186:187], off nt
	s_andn2_b64 vcc, exec, s[26:27]
	s_cbranch_vccnz .Ltr_k_nogain
	s_ashr_i32 s31, s30, 31
	v_lshl_add_u64 v[4:5], s[30:31], 0, v[12:13]
	v_lshl_add_u64 v[4:5], v[4:5], 2, s[60:61]
	global_load_dword v140, v[4:5], off
	global_load_dword v142, v[4:5], off offset:32
	global_load_dword v144, v[4:5], off offset:64
	global_load_dword v146, v[4:5], off offset:96
	global_load_dword v148, v[4:5], off offset:128
	global_load_dword v150, v[4:5], off offset:160
	global_load_dword v152, v[4:5], off offset:192
	global_load_dword v154, v[4:5], off offset:224
	s_waitcnt vmcnt(0)
	v_pk_mul_f32 v[108:109], v[108:109], v[140:141] op_sel_hi:[1,0]
	v_pk_mul_f32 v[110:111], v[110:111], v[140:141] op_sel_hi:[1,0]
	v_pk_mul_f32 v[112:113], v[112:113], v[142:143] op_sel_hi:[1,0]
	v_pk_mul_f32 v[114:115], v[114:115], v[142:143] op_sel_hi:[1,0]
	v_pk_mul_f32 v[116:117], v[116:117], v[144:145] op_sel_hi:[1,0]
	v_pk_mul_f32 v[118:119], v[118:119], v[144:145] op_sel_hi:[1,0]
	v_pk_mul_f32 v[120:121], v[120:121], v[146:147] op_sel_hi:[1,0]
	v_pk_mul_f32 v[122:123], v[122:123], v[146:147] op_sel_hi:[1,0]
	v_pk_mul_f32 v[124:125], v[124:125], v[148:149] op_sel_hi:[1,0]
	v_pk_mul_f32 v[126:127], v[126:127], v[148:149] op_sel_hi:[1,0]
	v_pk_mul_f32 v[128:129], v[128:129], v[150:151] op_sel_hi:[1,0]
	v_pk_mul_f32 v[130:131], v[130:131], v[150:151] op_sel_hi:[1,0]
	v_pk_mul_f32 v[132:133], v[132:133], v[152:153] op_sel_hi:[1,0]
	v_pk_mul_f32 v[134:135], v[134:135], v[152:153] op_sel_hi:[1,0]
	v_pk_mul_f32 v[136:137], v[136:137], v[154:155] op_sel_hi:[1,0]
	v_pk_mul_f32 v[138:139], v[138:139], v[154:155] op_sel_hi:[1,0]
